# same as previous stage A prefetch version, with wait-state padding kept in the second-pass copy (s_nop where loads were removed)
# speedup vs baseline: 1.0001x; 1.0001x over previous
; __device__ __forceinline__ float bf2f(bf16 v) { return __uint_as_float(((unsigned)v) << 16); }
; __device__ __forceinline__ float siluf_(float x) { return x * sigmoidf_(x); }
; template <int STRIP> __device__ __forceinline__ void ph_gdn_prep_fast(const bf16* __restrict__ proj, const float* __restrict__ small, const float* __restrict__ conv_w, const float* __restrict__ a_log, const float* __restrict__ dt_bias, ...
;     ...
;             for (int cs = 0; cs < 2; ++cs) {
;                 const int n = 2 * (pair & 31) + cs; const size_t m0 = (size_t)b * SEQ + n * 64;
;                 unsigned char* L = lds_dyn + cs * GP_CHUNK;
;                 const int tb = n * 64 + 4 * ts - 3;
;                 u32x2 xr[3][7];
; #pragma unroll
;                 for (int which = 0; which < 3; ++which)
; #pragma unroll
;                     for (int r = 0; r < 7; ++r) { const bool ok = tb + r >= 0; const bf16* src = proj + (m0 + 4 * ts - (ok ? 3 - r : 0)) * NPROJ + which * 768 + h * 128 + 4 * cg;
;                         xr[which][r] = *(const u32x2*)src; if (!ok) xr[which][r] = (u32x2){0u, 0u}; }
; #pragma unroll
;                 for (int which = 0; which < 3; ++which) {
;                     float xf[7][4];
; #pragma unroll
;                     for (int r = 0; r < 7; ++r) { xf[r][0] = bf2f((bf16)(xr[which][r].x & 0xffff)); xf[r][1] = bf2f((bf16)(xr[which][r].x >> 16)); xf[r][2] = bf2f((bf16)(xr[which][r].y & 0xffff)); xf[r][3] = bf2f((bf16)(xr[which][r].y >> 16)); }
; #pragma unroll
;                     for (int j = 0; j < 4; ++j) { float y[4]; float ss = 0.f;
; #pragma unroll
;                         for (int e = 0; e < 4; ++e) { float v = cw[which][0][e] * xf[j][e]; v += cw[which][1][e] * xf[j + 1][e]; v += cw[which][2][e] * xf[j + 2][e]; v += cw[which][3][e] * xf[j + 3][e]; y[e] = siluf_(v); ss += y[e] * y[e]; }
.Lsa_iter1:
	v_cndmask_b32_e64 v2, 0, 1, s[0:1]
	v_cmp_ne_u32_e64 s[4:5], 1, v2
	v_or_b32_e32 v2, s2, v53
	v_lshlrev_b32_e32 v2, 6, v2
	v_add_u32_e32 v84, v2, v56
	v_cmp_lt_i32_e64 s[8:9], 2, v84
	v_lshl_add_u64 v[76:77], v[58:59], 0, v[2:3]
	v_cmp_lt_i32_e64 s[14:15], 1, v84
	v_cndmask_b32_e64 v63, 0, -1, s[8:9]
	v_cndmask_b32_e64 v62, 0, -3, s[8:9]
	v_lshl_add_u64 v[62:63], v[62:63], 0, v[76:77]
	v_mad_u64_u32 v[66:67], s[0:1], v62, s23, v[60:61]
	v_mad_i32_i24 v67, v63, s23, v67
	s_nop 0
	v_cmp_lt_i32_e64 s[16:17], 0, v84
	v_mad_u64_u32 v[68:69], s[0:1], v76, s23, v[60:61]
	s_nop 0
	v_cndmask_b32_e64 v2, 0, 1, s[16:17]
	v_sub_co_u32_e32 v2, vcc, v76, v2
	v_mad_u64_u32 v[74:75], s[0:1], v2, s23, v[60:61]
	v_mad_i32_i24 v69, v77, s23, v69
	v_cmp_lt_i32_e64 s[10:11], -1, v84
	v_cmp_lt_i32_e64 s[6:7], -3, v84
	v_cmp_lt_i32_e64 s[12:13], -4, v84
	v_cndmask_b32_e64 v63, 0, -1, s[14:15]
	v_cndmask_b32_e64 v62, 0, -2, s[14:15]
	v_lshl_add_u64 v[62:63], v[62:63], 0, v[76:77]
	v_mad_u64_u32 v[70:71], s[0:1], v62, s23, v[60:61]
	v_mad_i32_i24 v71, v63, s23, v71
	s_nop 0
	v_subbrev_co_u32_e32 v62, vcc, 0, v77, vcc
	v_mad_i32_i24 v75, v62, s23, v75
	s_nop 0
	v_cmp_lt_i32_e32 vcc, -2, v84
	s_nop 0
	s_nop 0
	v_cndmask_b32_e64 v2, 0, 1, vcc
	v_or_b32_e32 v2, v76, v2
	v_mad_u64_u32 v[62:63], s[0:1], v2, s23, v[60:61]
	v_mad_i32_i24 v63, v77, s23, v63
	s_nop 0
	v_cndmask_b32_e64 v2, 0, 2, s[6:7]
	v_or_b32_e32 v2, v2, v76
	v_mad_u64_u32 v[64:65], s[0:1], v2, s23, v[60:61]
	v_mad_i32_i24 v65, v77, s23, v65
	s_nop 0
	v_cndmask_b32_e64 v2, 0, 3, s[12:13]
	v_or_b32_e32 v2, v2, v76
	v_mad_u64_u32 v[72:73], s[0:1], v2, s23, v[60:61]
	v_mad_i32_i24 v73, v77, s23, v73
	s_nop 0
	s_mul_i32 s0, s2, 0x11500
	v_add_u32_e32 v118, s0, v80
	s_mov_b32 s2, 1
	s_nop 0
	s_nop 0
	s_nop 0
	s_nop 0
	s_nop 0
	s_nop 0
	s_nop 0
	s_nop 0
	s_nop 0
	s_nop 0
	s_nop 0
	s_nop 0
	s_nop 0
	s_nop 0
	s_nop 0
	s_waitcnt vmcnt(0)
	v_cndmask_b32_e64 v119, 0, v186, s[8:9]
	v_cndmask_b32_e64 v122, 0, v187, s[8:9]
	v_cndmask_b32_e64 v120, 0, v188, s[14:15]
	v_cndmask_b32_e64 v124, 0, v189, s[14:15]
	v_cndmask_b32_e64 v121, 0, v190, s[16:17]
	v_cndmask_b32_e64 v125, 0, v191, s[16:17]
	v_cndmask_b32_e64 v87, 0, v192, s[10:11]
	v_cndmask_b32_e64 v123, 0, v193, s[10:11]
	v_cndmask_b32_e32 v116, 0, v194, vcc
	v_cndmask_b32_e32 v117, 0, v195, vcc
	v_cndmask_b32_e64 v113, 0, v196, s[6:7]
	v_cndmask_b32_e64 v115, 0, v197, s[6:7]
	v_cndmask_b32_e64 v2, 0, v198, s[12:13]
	v_cndmask_b32_e64 v114, 0, v199, s[12:13]
	v_cndmask_b32_e64 v106, 0, v200, s[8:9]
	v_cndmask_b32_e64 v110, 0, v201, s[8:9]
	v_cndmask_b32_e64 v107, 0, v202, s[14:15]
	v_cndmask_b32_e64 v111, 0, v203, s[14:15]
	v_cndmask_b32_e64 v108, 0, v204, s[16:17]
	v_cndmask_b32_e64 v112, 0, v205, s[16:17]
	v_cndmask_b32_e64 v105, 0, v206, s[10:11]
	v_cndmask_b32_e64 v109, 0, v207, s[10:11]
	v_cndmask_b32_e32 v103, 0, v208, vcc
	v_cndmask_b32_e32 v104, 0, v209, vcc
	v_cndmask_b32_e64 v88, 0, v210, s[8:9]
	v_cndmask_b32_e64 v95, 0, v211, s[8:9]
	v_cndmask_b32_e64 v89, 0, v212, s[14:15]
	v_cndmask_b32_e64 v96, 0, v213, s[14:15]
	v_cndmask_b32_e64 v94, 0, v216, s[16:17]
	v_cndmask_b32_e64 v98, 0, v217, s[16:17]
	v_and_b32_e32 v69, 0xffff0000, v124
	v_cndmask_b32_e64 v101, 0, v214, s[6:7]
	v_cndmask_b32_e64 v102, 0, v215, s[6:7]
	v_lshlrev_b32_e32 v68, 16, v124
	v_pk_mul_f32 v[70:71], v[6:7], v[68:69]
	v_cndmask_b32_e64 v91, 0, v218, s[10:11]
	v_cndmask_b32_e64 v97, 0, v219, s[10:11]
	v_cndmask_b32_e32 v92, 0, v220, vcc
	v_cndmask_b32_e32 v93, 0, v221, vcc
	v_and_b32_e32 v67, 0xffff0000, v122
	v_lshlrev_b32_e32 v66, 16, v122
	v_pk_fma_f32 v[66:67], v[14:15], v[66:67], v[70:71]
	v_and_b32_e32 v65, 0xffff0000, v123
	v_lshlrev_b32_e32 v64, 16, v123
	v_cndmask_b32_e64 v99, 0, v222, s[12:13]
	v_cndmask_b32_e64 v100, 0, v223, s[12:13]
	v_and_b32_e32 v77, 0xffff0000, v120
	v_and_b32_e32 v123, 0xffff0000, v119
	v_lshlrev_b32_e32 v122, 16, v119
	v_cndmask_b32_e64 v86, 0, v224, s[6:7]
	v_cndmask_b32_e64 v90, 0, v225, s[6:7]
	v_cndmask_b32_e64 v84, 0, v226, s[12:13]
	v_cndmask_b32_e64 v85, 0, v227, s[12:13]
